# idle-round capacity re-tune: 12 transposer items per wave in the layer-0 up-GEMM idle round
# speedup vs baseline: 1.0083x; 1.0083x over previous
.LBB0_1179:
	s_waitcnt vmcnt(0)
	s_barrier
	s_cmp_lt_u32 s96, 128
	s_cbranch_scc1 .LBB0_1180
	s_load_dwordx2 s[0:1], s[92:93], 0x58
	s_load_dwordx2 s[2:3], s[92:93], 0xb8
	s_load_dwordx2 s[4:5], s[92:93], 0xc0
	s_load_dwordx2 s[6:7], s[92:93], 0xc8
	s_load_dwordx2 s[8:9], s[92:93], 0xd0
	s_load_dwordx2 s[10:11], s[92:93], 0xe8
	v_and_b32_e32 v74, 63, v154
	v_lshrrev_b32_e32 v75, 6, v154
	v_mul_u32_u24_e32 v75, 0x2100, v75
	v_lshrrev_b32_e32 v3, 5, v74
	v_and_b32_e32 v4, 31, v74
	v_lshlrev_b32_e32 v4, 2, v4
	v_lshrrev_b32_e32 v5, 3, v74
	v_and_b32_e32 v6, 7, v74
	v_mul_u32_u24_e32 v2, 264, v6
	v_add_u32_e32 v2, v2, v5
	v_lshl_add_u32 v2, v2, 2, v75
	v_lshlrev_b32_e32 v6, 4, v6
	v_mul_u32_u24_e32 v1, 132, v5
	v_add3_u32 v1, v1, v6, v75
	v_readfirstlane_b32 s13, v154
	s_lshr_b32 s13, s13, 6
	s_lshl_b32 s26, s96, 3
	s_add_u32 s13, s13, s26
	s_sub_u32 s12, s13, 1024
	s_add_u32 s12, s12, 33280
	s_waitcnt lgkmcnt(0)
	s_cmp_ge_u32 s12, 45568
	s_cbranch_scc1 .Ltrs_done
	s_cmp_ge_u32 s12, 33280
	s_cselect_b32 s41, 1, 0
	s_cselect_b32 s26, 33280, 0
	s_sub_u32 s42, s12, s26
	s_cmp_ge_u32 s42, 12288
	s_cbranch_scc1 .Ltrs_m2
	s_mul_i32 s43, s42, 43691
	s_lshr_b32 s43, s43, 24
	s_mul_i32 s26, s43, 384
	s_sub_u32 s44, s42, s26
	s_mov_b32 s14, s0
	s_mov_b32 s15, s1
	s_mov_b32 s36, 0xc000
	s_mov_b32 s37, 0x6000000
	s_mov_b32 s38, 0x0
	s_mov_b32 s39, 0x3000000
	s_mov_b32 s40, 0x1000
	s_branch .Ltrs_dec_done1

.Ltrs_loop:
	s_add_u32 s12, s12, 1024
	s_cmp_lt_u32 s12, 45568
	s_cselect_b32 s24, 1, 0
	s_cbranch_scc0 .Ltrs_nonext8
	s_cmp_ge_u32 s12, 33280
	s_cselect_b32 s41, 1, 0
	s_cselect_b32 s26, 33280, 0
	s_sub_u32 s42, s12, s26
	s_cmp_ge_u32 s42, 12288
	s_cbranch_scc1 .Ltrs_m11
	s_mul_i32 s43, s42, 43691
	s_lshr_b32 s43, s43, 24
	s_mul_i32 s26, s43, 384
	s_sub_u32 s44, s42, s26
	s_mov_b32 s16, s0
	s_mov_b32 s17, s1
	s_mov_b32 s36, 0xc000
	s_mov_b32 s37, 0x6000000
	s_mov_b32 s38, 0x0
	s_mov_b32 s39, 0x3000000
	s_mov_b32 s40, 0x1000
	s_branch .Ltrs_dec_done10

.Ltrs_after9:
	ds_write_b32 v1, v10 offset:0
	ds_write_b32 v1, v11 offset:4
	ds_write_b32 v1, v12 offset:8
	ds_write_b32 v1, v13 offset:12
	ds_write_b32 v1, v14 offset:1056
	ds_write_b32 v1, v15 offset:1060
	ds_write_b32 v1, v16 offset:1064
	ds_write_b32 v1, v17 offset:1068
	ds_write_b32 v1, v18 offset:2112
	ds_write_b32 v1, v19 offset:2116
	ds_write_b32 v1, v20 offset:2120
	ds_write_b32 v1, v21 offset:2124
	ds_write_b32 v1, v22 offset:3168
	ds_write_b32 v1, v23 offset:3172
	ds_write_b32 v1, v24 offset:3176
	ds_write_b32 v1, v25 offset:3180
	ds_write_b32 v1, v26 offset:4224
	ds_write_b32 v1, v27 offset:4228
	ds_write_b32 v1, v28 offset:4232
	ds_write_b32 v1, v29 offset:4236
	ds_write_b32 v1, v30 offset:5280
	ds_write_b32 v1, v31 offset:5284
	ds_write_b32 v1, v32 offset:5288
	ds_write_b32 v1, v33 offset:5292
	ds_write_b32 v1, v34 offset:6336
	ds_write_b32 v1, v35 offset:6340
	ds_write_b32 v1, v36 offset:6344
	ds_write_b32 v1, v37 offset:6348
	ds_write_b32 v1, v38 offset:7392
	ds_write_b32 v1, v39 offset:7396
	ds_write_b32 v1, v40 offset:7400
	ds_write_b32 v1, v41 offset:7404
	v_mad_u32_u24 v9, v5, s22, v6
	s_lshl_b32 s46, s22, 3
	s_waitcnt lgkmcnt(0)
	ds_read_b32 v74, v2 offset:0
	ds_read_b32 v75, v2 offset:132
	ds_read_b32 v76, v2 offset:264
	ds_read_b32 v77, v2 offset:396
	ds_read_b32 v78, v2 offset:528
	ds_read_b32 v79, v2 offset:660
	ds_read_b32 v80, v2 offset:792
	ds_read_b32 v81, v2 offset:924
	ds_read_b32 v82, v2 offset:32
	ds_read_b32 v83, v2 offset:164
	ds_read_b32 v84, v2 offset:296
	ds_read_b32 v85, v2 offset:428
	ds_read_b32 v86, v2 offset:560
	ds_read_b32 v87, v2 offset:692
	ds_read_b32 v88, v2 offset:824
	ds_read_b32 v89, v2 offset:956
	s_waitcnt lgkmcnt(8)
	v_cvt_pk_bf16_f32 v106, v74, v75
	v_cvt_pk_bf16_f32 v107, v76, v77
	v_cvt_pk_bf16_f32 v108, v78, v79
	v_cvt_pk_bf16_f32 v109, v80, v81
	global_store_dwordx4 v9, v[106:109], s[18:19]
	s_add_u32 s18, s18, s46
	s_addc_u32 s19, s19, 0
	ds_read_b32 v90, v2 offset:64
	ds_read_b32 v91, v2 offset:196
	ds_read_b32 v92, v2 offset:328
	ds_read_b32 v93, v2 offset:460
	ds_read_b32 v94, v2 offset:592
	ds_read_b32 v95, v2 offset:724
	ds_read_b32 v96, v2 offset:856
	ds_read_b32 v97, v2 offset:988
	s_waitcnt lgkmcnt(8)
	v_cvt_pk_bf16_f32 v110, v82, v83
	v_cvt_pk_bf16_f32 v111, v84, v85
	v_cvt_pk_bf16_f32 v112, v86, v87
	v_cvt_pk_bf16_f32 v113, v88, v89
	global_store_dwordx4 v9, v[110:113], s[18:19]
	s_add_u32 s18, s18, s46
	s_addc_u32 s19, s19, 0
	ds_read_b32 v98, v2 offset:96
	ds_read_b32 v99, v2 offset:228
	ds_read_b32 v100, v2 offset:360
	ds_read_b32 v101, v2 offset:492
	ds_read_b32 v102, v2 offset:624
	ds_read_b32 v103, v2 offset:756
	ds_read_b32 v104, v2 offset:888
	ds_read_b32 v105, v2 offset:1020
	s_waitcnt lgkmcnt(8)
	v_cvt_pk_bf16_f32 v106, v90, v91
	v_cvt_pk_bf16_f32 v107, v92, v93
	v_cvt_pk_bf16_f32 v108, v94, v95
	v_cvt_pk_bf16_f32 v109, v96, v97
	global_store_dwordx4 v9, v[106:109], s[18:19]
	s_add_u32 s18, s18, s46
	s_addc_u32 s19, s19, 0
	s_waitcnt lgkmcnt(0)
	v_cvt_pk_bf16_f32 v110, v98, v99
	v_cvt_pk_bf16_f32 v111, v100, v101
	v_cvt_pk_bf16_f32 v112, v102, v103
	v_cvt_pk_bf16_f32 v113, v104, v105
	global_store_dwordx4 v9, v[110:113], s[18:19]
	s_cmp_eq_u32 s24, 0
	s_cbranch_scc1 .Ltrs_done
	s_add_u32 s12, s12, 1024
	s_cmp_lt_u32 s12, 45568
	s_cselect_b32 s24, 1, 0
	s_cbranch_scc0 .Ltrs_nonext17
	s_cmp_ge_u32 s12, 33280
	s_cselect_b32 s41, 1, 0
	s_cselect_b32 s26, 33280, 0
	s_sub_u32 s42, s12, s26
	s_cmp_ge_u32 s42, 12288
	s_cbranch_scc1 .Ltrs_m20
	s_mul_i32 s43, s42, 43691
	s_lshr_b32 s43, s43, 24
	s_mul_i32 s26, s43, 384
	s_sub_u32 s44, s42, s26
	s_mov_b32 s14, s0
	s_mov_b32 s15, s1
	s_mov_b32 s36, 0xc000
	s_mov_b32 s37, 0x6000000
	s_mov_b32 s38, 0x0
	s_mov_b32 s39, 0x3000000
	s_mov_b32 s40, 0x1000
	s_branch .Ltrs_dec_done19

.LBB0_1734:
	s_cmp_lt_u32 s96, 128
	s_cbranch_scc1 .Lmix1_skip
	s_load_dwordx2 s[0:1], s[92:93], 0x58
	s_load_dwordx2 s[2:3], s[92:93], 0xb8
	s_load_dwordx2 s[4:5], s[92:93], 0xc0
	s_load_dwordx2 s[6:7], s[92:93], 0xc8
	s_load_dwordx2 s[8:9], s[92:93], 0xd0
	s_load_dwordx2 s[10:11], s[92:93], 0xe8
	v_and_b32_e32 v74, 63, v154
	v_lshrrev_b32_e32 v75, 6, v154
	v_mul_u32_u24_e32 v75, 0x2100, v75
	v_lshrrev_b32_e32 v3, 5, v74
	v_and_b32_e32 v4, 31, v74
	v_lshlrev_b32_e32 v4, 2, v4
	v_lshrrev_b32_e32 v5, 3, v74
	v_and_b32_e32 v6, 7, v74
	v_mul_u32_u24_e32 v2, 264, v6
	v_add_u32_e32 v2, v2, v5
	v_lshl_add_u32 v2, v2, 2, v75
	v_lshlrev_b32_e32 v6, 4, v6
	v_mul_u32_u24_e32 v1, 132, v5
	v_add3_u32 v1, v1, v6, v75
	v_readfirstlane_b32 s13, v154
	s_lshr_b32 s13, s13, 6
	s_lshl_b32 s26, s96, 3
	s_add_u32 s13, s13, s26
	s_sub_u32 s12, s13, 1024
	s_add_u32 s12, s12, 45568
	s_waitcnt lgkmcnt(0)
	s_cmp_ge_u32 s12, 60928
	s_cbranch_scc1 .Ltrn_done
	s_cmp_ge_u32 s12, 33280
	s_cselect_b32 s41, 1, 0
	s_cselect_b32 s26, 33280, 0
	s_sub_u32 s42, s12, s26
	s_cmp_ge_u32 s42, 12288
	s_cbranch_scc1 .Ltrn_m2
	s_mul_i32 s43, s42, 43691
	s_lshr_b32 s43, s43, 24
	s_mul_i32 s26, s43, 384
	s_sub_u32 s44, s42, s26
	s_mov_b32 s14, s0
	s_mov_b32 s15, s1
	s_mov_b32 s36, 0xc000
	s_mov_b32 s37, 0x6000000
	s_mov_b32 s38, 0x0
	s_mov_b32 s39, 0x3000000
	s_mov_b32 s40, 0x1000
	s_branch .Ltrn_dec_done1
